# v6 + P9 sample-row mini GEMM (K=2816): 33 operand loads issued together with one wait instead of hipcc load/wait ladder
# baseline (speedup 1.0000x reference)
;     ...
;         for (int s0 = 0; s0 < nsw; s0 += KS) {
;             bf16x8 a[KS][NRB], b[KS], c[KS];
; #pragma unroll
;             for (int s = 0; s < KS; ++s) { const bool on = s0 + s < nsw; const int ko = (s0 + s) * 32;
;                 b[s] = on ? *(const bf16x8*)(bp + ko) : (bf16x8){0, 0, 0, 0, 0, 0, 0, 0}; if (TWO) c[s] = on ? *(const bf16x8*)(bp + (size_t)128 * K + ko) : (bf16x8){0, 0, 0, 0, 0, 0, 0, 0};
; #pragma unroll
;                 for (int r = 0; r < NRB; ++r) a[s][r] = on ? *(const bf16x8*)(ap + (size_t)(16 * r) * K + ko) : (bf16x8){0, 0, 0, 0, 0, 0, 0, 0}; }
; #pragma unroll
;             for (int s = 0; s < KS; ++s)
; #pragma unroll
;                 for (int r = 0; r < NRB; ++r) { acc0[r] = __builtin_amdgcn_mfma_f32_16x16x32_bf16(b[s], a[s][r], acc0[r], 0, 0, 0); if (TWO) acc1[r] = __builtin_amdgcn_mfma_f32_16x16x32_bf16(c[s], a[s][r], acc1[r], 0, 0, 0); }
;         }
;         f32x4 t0 = (f32x4){0.f, 0.f, 0.f, 0.f}, t1 = (f32x4){0.f, 0.f, 0.f, 0.f};
; #pragma unroll
;         for (int r = 0; r < NRB; ++r) red[(wave * NRB + r) * 64 + lane] = acc0[r];
;         __syncthreads();
;         if (wave < NRB) {
; #pragma unroll
;             for (int s = 0; s < 8; ++s) t0 += red[(s * NRB + wave) * 64 + lane]; }
.LBB0_1111:
	s_ashr_i32 s6, s3, 31
	s_lshr_b32 s7, s6, 26
	s_add_i32 s7, s3, s7
	s_ashr_i32 s8, s7, 6
	s_lshr_b32 s7, s8, 30
	s_lshr_b32 s6, s6, 24
	s_add_i32 s7, s8, s7
	s_add_i32 s6, s3, s6
	s_and_b32 s7, s7, 0x7fffffc
	s_ashr_i32 s6, s6, 8
	s_sub_i32 s7, s8, s7
	s_lshl_b32 s6, s6, 7
	s_lshl_b32 s7, s7, 5
	s_add_i32 s9, s6, s7
	s_mul_i32 s6, s8, 0xffd40000
	v_add_u32_e32 v8, s6, v17
	v_ashrrev_i32_e32 v9, 31, v8
	v_lshl_add_u64 v[12:13], v[8:9], 1, v[6:7]
	s_addk_i32 s9, 0x4000
	v_or_b32_e32 v20, s9, v148
	v_mad_i64_i32 v[64:65], s[6:7], v20, s22, v[4:5]
	v_add_co_u32_e32 v66, vcc, s23, v64
	s_nop 1
	v_addc_co_u32_e32 v67, vcc, 0, v65, vcc
	global_load_dwordx4 v[68:71], v[12:13], off
	global_load_dwordx4 v[72:75], v[64:65], off
	global_load_dwordx4 v[76:79], v[66:67], off
	global_load_dwordx4 v[80:83], v[12:13], off offset:64
	global_load_dwordx4 v[84:87], v[64:65], off offset:64
	global_load_dwordx4 v[88:91], v[66:67], off offset:64
	global_load_dwordx4 v[92:95], v[12:13], off offset:128
	global_load_dwordx4 v[96:99], v[64:65], off offset:128
	global_load_dwordx4 v[100:103], v[12:13], off offset:192
	global_load_dwordx4 v[104:107], v[64:65], off offset:640
	global_load_dwordx4 v[108:111], v[66:67], off offset:128
	global_load_dwordx4 v[112:115], v[64:65], off offset:192
	global_load_dwordx4 v[116:119], v[12:13], off offset:256
	global_load_dwordx4 v[120:123], v[66:67], off offset:192
	global_load_dwordx4 v[124:127], v[64:65], off offset:256
	global_load_dwordx4 v[132:135], v[66:67], off offset:256
	global_load_dwordx4 v[136:139], v[12:13], off offset:320
	global_load_dwordx4 v[140:143], v[64:65], off offset:320
	global_load_dwordx4 v[144:147], v[66:67], off offset:320
	global_load_dwordx4 v[156:159], v[12:13], off offset:384
	global_load_dwordx4 v[164:167], v[64:65], off offset:384
	global_load_dwordx4 v[168:171], v[12:13], off offset:448
	global_load_dwordx4 v[172:175], v[66:67], off offset:384
	global_load_dwordx4 v[176:179], v[64:65], off offset:448
	global_load_dwordx4 v[180:183], v[66:67], off offset:448
	global_load_dwordx4 v[184:187], v[12:13], off offset:512
	global_load_dwordx4 v[188:191], v[64:65], off offset:512
	global_load_dwordx4 v[192:195], v[66:67], off offset:512
	global_load_dwordx4 v[196:199], v[64:65], off offset:576
	global_load_dwordx4 v[200:203], v[12:13], off offset:576
	global_load_dwordx4 v[204:207], v[66:67], off offset:576
	global_load_dwordx4 v[208:211], v[12:13], off offset:640
	global_load_dwordx4 v[212:215], v[66:67], off offset:640
	s_waitcnt vmcnt(0)
	s_waitcnt lgkmcnt(0)
	v_mfma_f32_16x16x32_bf16 v[20:23], v[68:71], v[72:75], 0
	v_mfma_f32_16x16x32_bf16 v[8:11], v[68:71], v[76:79], 0
	v_mfma_f32_16x16x32_bf16 v[20:23], v[80:83], v[84:87], v[20:23]
	v_mfma_f32_16x16x32_bf16 v[8:11], v[80:83], v[88:91], v[8:11]
	v_mfma_f32_16x16x32_bf16 v[20:23], v[92:95], v[96:99], v[20:23]
	v_mfma_f32_16x16x32_bf16 v[8:11], v[92:95], v[108:111], v[8:11]
	v_mfma_f32_16x16x32_bf16 v[20:23], v[100:103], v[112:115], v[20:23]
	v_mfma_f32_16x16x32_bf16 v[8:11], v[100:103], v[120:123], v[8:11]
	v_mfma_f32_16x16x32_bf16 v[20:23], v[116:119], v[124:127], v[20:23]
	v_mfma_f32_16x16x32_bf16 v[8:11], v[116:119], v[132:135], v[8:11]
	v_mfma_f32_16x16x32_bf16 v[20:23], v[136:139], v[140:143], v[20:23]
	v_mfma_f32_16x16x32_bf16 v[8:11], v[136:139], v[144:147], v[8:11]
	v_mfma_f32_16x16x32_bf16 v[20:23], v[156:159], v[164:167], v[20:23]
	v_mfma_f32_16x16x32_bf16 v[8:11], v[156:159], v[172:175], v[8:11]
	v_mfma_f32_16x16x32_bf16 v[20:23], v[168:171], v[176:179], v[20:23]
	v_mfma_f32_16x16x32_bf16 v[8:11], v[168:171], v[180:183], v[8:11]
	v_mfma_f32_16x16x32_bf16 v[20:23], v[184:187], v[188:191], v[20:23]
	v_mfma_f32_16x16x32_bf16 v[8:11], v[184:187], v[192:195], v[8:11]
	v_mfma_f32_16x16x32_bf16 v[20:23], v[200:203], v[196:199], v[20:23]
	v_mfma_f32_16x16x32_bf16 v[8:11], v[200:203], v[204:207], v[8:11]
	v_mfma_f32_16x16x32_bf16 v[20:23], v[208:211], v[104:107], v[20:23]
	v_mfma_f32_16x16x32_bf16 v[24:27], v[208:211], v[212:215], v[8:11]
	s_nop 2
	v_mov_b32_e32 v10, 0
	v_mov_b32_e32 v11, 0
	v_mov_b32_e32 v8, 0
	v_mfma_f32_16x16x32_bf16 v[20:23], v[0:3], v[0:3], v[20:23]
	v_mov_b32_e32 v9, 0
	v_mfma_f32_16x16x32_bf16 v[24:27], v[0:3], v[0:3], v[24:27]
	s_nop 5
	ds_write_b128 v18, v[20:23]
	s_nop 0
	ds_write_b128 v18, v[24:27] offset:1024
	s_waitcnt lgkmcnt(0)
	s_barrier
	s_and_saveexec_b64 s[6:7], s[0:1]
	s_cbranch_execz .LBB0_1113
	ds_read_b128 v[8:11], v14
	ds_read_b128 v[20:23], v14 offset:2048
	ds_read_b128 v[24:27], v14 offset:4096
	ds_read_b128 v[28:31], v14 offset:6144
	s_waitcnt lgkmcnt(3)
	v_pk_add_f32 v[10:11], v[10:11], 0 op_sel_hi:[1,0]
	v_pk_add_f32 v[8:9], v[8:9], 0 op_sel_hi:[1,0]
	s_waitcnt lgkmcnt(2)
	v_pk_add_f32 v[10:11], v[10:11], v[22:23]
	v_pk_add_f32 v[12:13], v[8:9], v[20:21]
	s_waitcnt lgkmcnt(1)
	v_pk_add_f32 v[20:21], v[10:11], v[26:27]
	ds_read_b128 v[8:11], v14 offset:8192
	v_pk_add_f32 v[12:13], v[12:13], v[24:25]
	s_waitcnt lgkmcnt(1)
	v_pk_add_f32 v[24:25], v[20:21], v[30:31]
	ds_read_b128 v[20:23], v14 offset:10240
	v_pk_add_f32 v[26:27], v[12:13], v[28:29]
	s_waitcnt lgkmcnt(1)
	v_pk_add_f32 v[28:29], v[24:25], v[10:11]
	ds_read_b128 v[10:13], v14 offset:12288
	v_pk_add_f32 v[8:9], v[26:27], v[8:9]
	ds_read_b128 v[24:27], v14 offset:14336
	s_waitcnt lgkmcnt(2)
	v_pk_add_f32 v[22:23], v[28:29], v[22:23]
	v_pk_add_f32 v[8:9], v[8:9], v[20:21]
	s_waitcnt lgkmcnt(1)
	v_pk_add_f32 v[12:13], v[22:23], v[12:13]
	v_pk_add_f32 v[10:11], v[8:9], v[10:11]
	s_waitcnt lgkmcnt(0)
	v_pk_add_f32 v[8:9], v[12:13], v[26:27]
	v_pk_add_f32 v[10:11], v[10:11], v[24:25]
